# GU unit exit: the older wave half's re-alignment barrier moved from before the epilogue to after its first row group (works in the younger half's last MFMA interval)
# baseline (speedup 1.0000x reference)
; #define PG8_BAR __builtin_amdgcn_s_barrier()
; __device__ __forceinline__ unsigned pk2(float lo, float hi) { unsigned r; asm("v_cvt_pk_bf16_f32 %0, %1, %2" : "=v"(r) : "v"(lo), "v"(hi)); return r; }
; __device__ __forceinline__ float silu_f(float x) { return x * sigmoid_f(x); }
; template <class Epi, class Sched, bool ALIGN_EPI = false, bool SP2 = false>
; __device__ __forceinline__ void gemm_phase(PG8_LAS unsigned char* lds, const Gemm g, const Sched& S, const Epi& E, const int wave_s) {
;     ...
;         if constexpr (ALIGN_EPI) { if (wr == 0) PG8_BAR; }
;     __device__ __forceinline__ void operator()(const f32x4 (&acc)[2][2][4][2], const pg8::Unit& u, int wr, int wc, int fr, int fq) const {
;         const int row0 = u.pm * 256 + wr * 64 + fr, col0 = u.pn * 128 + wc * 32 + 8 * fq;
;         float rs[2][4];
; #pragma unroll
;         for (int ai = 0; ai < 2; ++ai)
; #pragma unroll
;             for (int m = 0; m < 4; ++m) rs[ai][m] = ss[row0 + ai * 128 + m * 16];
; #pragma unroll
;         for (int ai = 0; ai < 2; ++ai)
; #pragma unroll
;             for (int m = 0; m < 4; ++m) {
;                 const int r = row0 + ai * 128 + m * 16;
;                 const float rstd = __builtin_amdgcn_rsqf(rs[ai][m] * (1.0f / D) + EPS);
;                 float o[8];
; #pragma unroll
;                 for (int n = 0; n < 2; ++n)
; #pragma unroll
;                     for (int e = 0; e < 4; ++e) { const float g = acc[ai][0][m][n][e] * rstd, up = acc[ai][1][m][n][e] * rstd; o[4 * n + e] = silu_f(g) * up; }
;                 u32x4 w; w.x = pk2(o[0], o[1]); w.y = pk2(o[2], o[3]); w.z = pk2(o[4], o[5]); w.w = pk2(o[6], o[7]);
;                 *(u32x4*)(ACT + (size_t)r * FF + col0) = w;
.LBB0_526:
	s_lshl_b32 s2, s45, 8
	s_add_i32 s2, s2, s39
	v_add_u32_e32 v140, s2, v145
	v_lshlrev_b32_e32 v141, 2, v140
	global_load_dword v150, v141, s[12:13]
	global_load_dword v152, v141, s[12:13] offset:64
	global_load_dword v154, v141, s[12:13] offset:128
	global_load_dword v156, v141, s[12:13] offset:192
	global_load_dword v158, v141, s[12:13] offset:512
	global_load_dword v160, v141, s[12:13] offset:576
	global_load_dword v144, v141, s[12:13] offset:640
	global_load_dword v174, v141, s[12:13] offset:704
	s_lshl_b32 s2, s44, 7
	s_or_b32 s2, s2, s40
	v_lshl_add_u32 v142, v146, 3, s2
	s_movk_i32 s17, 0x1600
	v_mul_lo_u32 v171, v140, s17
	v_lshl_add_u32 v171, v142, 1, v171
	s_mov_b32 s2, 0xbfb8aa3b
	s_waitcnt vmcnt(0)
	v_fmamk_f32 v150, v150, 0x3a800000, v199
	v_fmamk_f32 v152, v152, 0x3a800000, v199
	v_fmamk_f32 v154, v154, 0x3a800000, v199
	v_fmamk_f32 v156, v156, 0x3a800000, v199
	v_fmamk_f32 v158, v158, 0x3a800000, v199
	v_fmamk_f32 v160, v160, 0x3a800000, v199
	v_fmamk_f32 v144, v144, 0x3a800000, v199
	v_fmamk_f32 v174, v174, 0x3a800000, v199
	v_rsq_f32_e32 v150, v150
	v_rsq_f32_e32 v152, v152
	v_rsq_f32_e32 v154, v154
	v_rsq_f32_e32 v156, v156
	v_rsq_f32_e32 v158, v158
	v_rsq_f32_e32 v160, v160
	v_rsq_f32_e32 v144, v144
	v_rsq_f32_e32 v174, v174
	v_pk_mul_f32 v[124:125], v[124:125], v[150:151] op_sel_hi:[1,0]
	v_pk_mul_f32 v[120:121], v[120:121], v[150:151] op_sel_hi:[1,0]
	v_pk_mul_f32 v[126:127], v[126:127], v[150:151] op_sel_hi:[1,0]
	v_pk_mul_f32 v[122:123], v[122:123], v[150:151] op_sel_hi:[1,0]
	v_pk_mul_f32 v[140:141], v[124:125], s[2:3] op_sel_hi:[1,0]
	v_pk_mul_f32 v[142:143], v[126:127], s[2:3] op_sel_hi:[1,0]
	v_exp_f32_e32 v140, v140
	v_exp_f32_e32 v141, v141
	v_exp_f32_e32 v142, v142
	v_exp_f32_e32 v143, v143
	v_pk_add_f32 v[140:141], v[140:141], 1.0 op_sel_hi:[1,0]
	v_pk_add_f32 v[142:143], v[142:143], 1.0 op_sel_hi:[1,0]
	v_rcp_f32_e32 v140, v140
	v_rcp_f32_e32 v141, v141
	v_rcp_f32_e32 v142, v142
	v_rcp_f32_e32 v143, v143
	v_pk_mul_f32 v[124:125], v[124:125], v[140:141]
	v_pk_mul_f32 v[126:127], v[126:127], v[142:143]
	v_pk_mul_f32 v[124:125], v[124:125], v[120:121]
	v_pk_mul_f32 v[126:127], v[126:127], v[122:123]
	v_pk_mul_f32 v[116:117], v[116:117], v[150:151] op_sel_hi:[1,0]
	v_pk_mul_f32 v[112:113], v[112:113], v[150:151] op_sel_hi:[1,0]
	v_pk_mul_f32 v[118:119], v[118:119], v[150:151] op_sel_hi:[1,0]
	v_pk_mul_f32 v[114:115], v[114:115], v[150:151] op_sel_hi:[1,0]
	v_pk_mul_f32 v[140:141], v[116:117], s[2:3] op_sel_hi:[1,0]
	v_pk_mul_f32 v[142:143], v[118:119], s[2:3] op_sel_hi:[1,0]
	v_exp_f32_e32 v140, v140
	v_exp_f32_e32 v141, v141
	v_exp_f32_e32 v142, v142
	v_exp_f32_e32 v143, v143
	v_pk_add_f32 v[140:141], v[140:141], 1.0 op_sel_hi:[1,0]
	v_pk_add_f32 v[142:143], v[142:143], 1.0 op_sel_hi:[1,0]
	v_rcp_f32_e32 v140, v140
	v_rcp_f32_e32 v141, v141
	v_rcp_f32_e32 v142, v142
	v_rcp_f32_e32 v143, v143
	v_pk_mul_f32 v[116:117], v[116:117], v[140:141]
	v_pk_mul_f32 v[118:119], v[118:119], v[142:143]
	v_pk_mul_f32 v[116:117], v[116:117], v[112:113]
	v_pk_mul_f32 v[118:119], v[118:119], v[114:115]
	v_cvt_pk_bf16_f32 v124, v124, v125
	v_cvt_pk_bf16_f32 v125, v126, v127
	v_cvt_pk_bf16_f32 v126, v116, v117
	v_cvt_pk_bf16_f32 v127, v118, v119
	global_store_dwordx4 v171, v[124:127], s[10:11]
	s_and_b64 vcc, exec, s[14:15]
	s_cbranch_vccz .Lgu_late_e
	s_barrier
.Lgu_late_e:
	v_pk_mul_f32 v[108:109], v[108:109], v[152:153] op_sel_hi:[1,0]
	v_pk_mul_f32 v[104:105], v[104:105], v[152:153] op_sel_hi:[1,0]
	v_pk_mul_f32 v[110:111], v[110:111], v[152:153] op_sel_hi:[1,0]
	v_pk_mul_f32 v[106:107], v[106:107], v[152:153] op_sel_hi:[1,0]
	v_pk_mul_f32 v[140:141], v[108:109], s[2:3] op_sel_hi:[1,0]
	v_pk_mul_f32 v[142:143], v[110:111], s[2:3] op_sel_hi:[1,0]
	v_exp_f32_e32 v140, v140
	v_exp_f32_e32 v141, v141
	v_exp_f32_e32 v142, v142
	v_exp_f32_e32 v143, v143
	v_pk_add_f32 v[140:141], v[140:141], 1.0 op_sel_hi:[1,0]
	v_pk_add_f32 v[142:143], v[142:143], 1.0 op_sel_hi:[1,0]
	v_rcp_f32_e32 v140, v140
	v_rcp_f32_e32 v141, v141
	v_rcp_f32_e32 v142, v142
	v_rcp_f32_e32 v143, v143
	v_pk_mul_f32 v[108:109], v[108:109], v[140:141]
	v_pk_mul_f32 v[110:111], v[110:111], v[142:143]
	v_pk_mul_f32 v[108:109], v[108:109], v[104:105]
	v_pk_mul_f32 v[110:111], v[110:111], v[106:107]
	v_pk_mul_f32 v[100:101], v[100:101], v[152:153] op_sel_hi:[1,0]
	v_pk_mul_f32 v[96:97], v[96:97], v[152:153] op_sel_hi:[1,0]
	v_pk_mul_f32 v[102:103], v[102:103], v[152:153] op_sel_hi:[1,0]
	v_pk_mul_f32 v[98:99], v[98:99], v[152:153] op_sel_hi:[1,0]
	v_pk_mul_f32 v[140:141], v[100:101], s[2:3] op_sel_hi:[1,0]
	v_pk_mul_f32 v[142:143], v[102:103], s[2:3] op_sel_hi:[1,0]
	v_exp_f32_e32 v140, v140
	v_exp_f32_e32 v141, v141
	v_exp_f32_e32 v142, v142
	v_exp_f32_e32 v143, v143
	v_pk_add_f32 v[140:141], v[140:141], 1.0 op_sel_hi:[1,0]
	v_pk_add_f32 v[142:143], v[142:143], 1.0 op_sel_hi:[1,0]
	v_rcp_f32_e32 v140, v140
	v_rcp_f32_e32 v141, v141
	v_rcp_f32_e32 v142, v142
	v_rcp_f32_e32 v143, v143
	v_pk_mul_f32 v[100:101], v[100:101], v[140:141]
	v_pk_mul_f32 v[102:103], v[102:103], v[142:143]
	v_pk_mul_f32 v[100:101], v[100:101], v[96:97]
	v_pk_mul_f32 v[102:103], v[102:103], v[98:99]
	v_cvt_pk_bf16_f32 v108, v108, v109
	v_cvt_pk_bf16_f32 v109, v110, v111
	v_cvt_pk_bf16_f32 v110, v100, v101
	v_cvt_pk_bf16_f32 v111, v102, v103
	v_add_u32_e32 v149, 0x16000, v171
	global_store_dwordx4 v149, v[108:111], s[10:11]
	v_pk_mul_f32 v[92:93], v[92:93], v[154:155] op_sel_hi:[1,0]
	v_pk_mul_f32 v[88:89], v[88:89], v[154:155] op_sel_hi:[1,0]
	v_pk_mul_f32 v[94:95], v[94:95], v[154:155] op_sel_hi:[1,0]
	v_pk_mul_f32 v[90:91], v[90:91], v[154:155] op_sel_hi:[1,0]
; __device__ __forceinline__ unsigned pk2(float lo, float hi) { unsigned r; asm("v_cvt_pk_bf16_f32 %0, %1, %2" : "=v"(r) : "v"(lo), "v"(hi)); return r; }
; __device__ __forceinline__ float silu_f(float x) { return x * sigmoid_f(x); }
;     __device__ __forceinline__ void operator()(const f32x4 (&acc)[2][2][4][2], const pg8::Unit& u, int wr, int wc, int fr, int fq) const {
;     ...
;         for (int ai = 0; ai < 2; ++ai)
; #pragma unroll
;             for (int m = 0; m < 4; ++m) {
;                 const int r = row0 + ai * 128 + m * 16;
;                 const float rstd = __builtin_amdgcn_rsqf(rs[ai][m] * (1.0f / D) + EPS);
;                 float o[8];
; #pragma unroll
;                 for (int n = 0; n < 2; ++n)
; #pragma unroll
;                     for (int e = 0; e < 4; ++e) { const float g = acc[ai][0][m][n][e] * rstd, up = acc[ai][1][m][n][e] * rstd; o[4 * n + e] = silu_f(g) * up; }
;                 u32x4 w; w.x = pk2(o[0], o[1]); w.y = pk2(o[2], o[3]); w.z = pk2(o[4], o[5]); w.w = pk2(o[6], o[7]);
;                 *(u32x4*)(ACT + (size_t)r * FF + col0) = w;
	v_pk_mul_f32 v[140:141], v[92:93], s[2:3] op_sel_hi:[1,0]
	v_pk_mul_f32 v[142:143], v[94:95], s[2:3] op_sel_hi:[1,0]
	v_exp_f32_e32 v140, v140
	v_exp_f32_e32 v141, v141
	v_exp_f32_e32 v142, v142
	v_exp_f32_e32 v143, v143
	v_pk_add_f32 v[140:141], v[140:141], 1.0 op_sel_hi:[1,0]
	v_pk_add_f32 v[142:143], v[142:143], 1.0 op_sel_hi:[1,0]
	v_rcp_f32_e32 v140, v140
	v_rcp_f32_e32 v141, v141
	v_rcp_f32_e32 v142, v142
	v_rcp_f32_e32 v143, v143
	v_pk_mul_f32 v[92:93], v[92:93], v[140:141]
	v_pk_mul_f32 v[94:95], v[94:95], v[142:143]
	v_pk_mul_f32 v[92:93], v[92:93], v[88:89]
	v_pk_mul_f32 v[94:95], v[94:95], v[90:91]
	v_pk_mul_f32 v[84:85], v[84:85], v[154:155] op_sel_hi:[1,0]
	v_pk_mul_f32 v[80:81], v[80:81], v[154:155] op_sel_hi:[1,0]
	v_pk_mul_f32 v[86:87], v[86:87], v[154:155] op_sel_hi:[1,0]
	v_pk_mul_f32 v[82:83], v[82:83], v[154:155] op_sel_hi:[1,0]
	v_pk_mul_f32 v[140:141], v[84:85], s[2:3] op_sel_hi:[1,0]
	v_pk_mul_f32 v[142:143], v[86:87], s[2:3] op_sel_hi:[1,0]
	v_exp_f32_e32 v140, v140
	v_exp_f32_e32 v141, v141
	v_exp_f32_e32 v142, v142
	v_exp_f32_e32 v143, v143
	v_pk_add_f32 v[140:141], v[140:141], 1.0 op_sel_hi:[1,0]
	v_pk_add_f32 v[142:143], v[142:143], 1.0 op_sel_hi:[1,0]
	v_rcp_f32_e32 v140, v140
	v_rcp_f32_e32 v141, v141
	v_rcp_f32_e32 v142, v142
	v_rcp_f32_e32 v143, v143
	v_pk_mul_f32 v[84:85], v[84:85], v[140:141]
	v_pk_mul_f32 v[86:87], v[86:87], v[142:143]
	v_pk_mul_f32 v[84:85], v[84:85], v[80:81]
	v_pk_mul_f32 v[86:87], v[86:87], v[82:83]
	v_cvt_pk_bf16_f32 v92, v92, v93
	v_cvt_pk_bf16_f32 v93, v94, v95
	v_cvt_pk_bf16_f32 v94, v84, v85
	v_cvt_pk_bf16_f32 v95, v86, v87
	v_add_u32_e32 v149, 0x2c000, v171
	global_store_dwordx4 v149, v[92:95], s[10:11]
	v_pk_mul_f32 v[76:77], v[76:77], v[156:157] op_sel_hi:[1,0]
	v_pk_mul_f32 v[72:73], v[72:73], v[156:157] op_sel_hi:[1,0]
	v_pk_mul_f32 v[78:79], v[78:79], v[156:157] op_sel_hi:[1,0]
	v_pk_mul_f32 v[74:75], v[74:75], v[156:157] op_sel_hi:[1,0]
	v_pk_mul_f32 v[140:141], v[76:77], s[2:3] op_sel_hi:[1,0]
	v_pk_mul_f32 v[142:143], v[78:79], s[2:3] op_sel_hi:[1,0]
	v_exp_f32_e32 v140, v140
	v_exp_f32_e32 v141, v141
	v_exp_f32_e32 v142, v142
	v_exp_f32_e32 v143, v143
	v_pk_add_f32 v[140:141], v[140:141], 1.0 op_sel_hi:[1,0]
	v_pk_add_f32 v[142:143], v[142:143], 1.0 op_sel_hi:[1,0]
	v_rcp_f32_e32 v140, v140
	v_rcp_f32_e32 v141, v141
	v_rcp_f32_e32 v142, v142
	v_rcp_f32_e32 v143, v143
	v_pk_mul_f32 v[76:77], v[76:77], v[140:141]
	v_pk_mul_f32 v[78:79], v[78:79], v[142:143]
	v_pk_mul_f32 v[76:77], v[76:77], v[72:73]
	v_pk_mul_f32 v[78:79], v[78:79], v[74:75]
	v_pk_mul_f32 v[68:69], v[68:69], v[156:157] op_sel_hi:[1,0]
	v_pk_mul_f32 v[64:65], v[64:65], v[156:157] op_sel_hi:[1,0]
	v_pk_mul_f32 v[70:71], v[70:71], v[156:157] op_sel_hi:[1,0]
	v_pk_mul_f32 v[66:67], v[66:67], v[156:157] op_sel_hi:[1,0]
	v_pk_mul_f32 v[140:141], v[68:69], s[2:3] op_sel_hi:[1,0]
	v_pk_mul_f32 v[142:143], v[70:71], s[2:3] op_sel_hi:[1,0]
	v_exp_f32_e32 v140, v140
	v_exp_f32_e32 v141, v141
	v_exp_f32_e32 v142, v142
	v_exp_f32_e32 v143, v143
	v_pk_add_f32 v[140:141], v[140:141], 1.0 op_sel_hi:[1,0]
	v_pk_add_f32 v[142:143], v[142:143], 1.0 op_sel_hi:[1,0]
	v_rcp_f32_e32 v140, v140
	v_rcp_f32_e32 v141, v141
	v_rcp_f32_e32 v142, v142
	v_rcp_f32_e32 v143, v143
	v_pk_mul_f32 v[68:69], v[68:69], v[140:141]
	v_pk_mul_f32 v[70:71], v[70:71], v[142:143]
	v_pk_mul_f32 v[68:69], v[68:69], v[64:65]
	v_pk_mul_f32 v[70:71], v[70:71], v[66:67]
	v_cvt_pk_bf16_f32 v76, v76, v77
	v_cvt_pk_bf16_f32 v77, v78, v79
	v_cvt_pk_bf16_f32 v78, v68, v69
	v_cvt_pk_bf16_f32 v79, v70, v71
	v_add_u32_e32 v149, 0x42000, v171
	global_store_dwordx4 v149, v[76:79], s[10:11]
	v_pk_mul_f32 v[60:61], v[60:61], v[158:159] op_sel_hi:[1,0]
	v_pk_mul_f32 v[56:57], v[56:57], v[158:159] op_sel_hi:[1,0]
	v_pk_mul_f32 v[62:63], v[62:63], v[158:159] op_sel_hi:[1,0]
	v_pk_mul_f32 v[58:59], v[58:59], v[158:159] op_sel_hi:[1,0]
	v_pk_mul_f32 v[140:141], v[60:61], s[2:3] op_sel_hi:[1,0]
	v_pk_mul_f32 v[142:143], v[62:63], s[2:3] op_sel_hi:[1,0]
	v_exp_f32_e32 v140, v140
	v_exp_f32_e32 v141, v141
	v_exp_f32_e32 v142, v142
	v_exp_f32_e32 v143, v143
	v_pk_add_f32 v[140:141], v[140:141], 1.0 op_sel_hi:[1,0]
	v_pk_add_f32 v[142:143], v[142:143], 1.0 op_sel_hi:[1,0]
	v_rcp_f32_e32 v140, v140
	v_rcp_f32_e32 v141, v141
	v_rcp_f32_e32 v142, v142
	v_rcp_f32_e32 v143, v143
	v_pk_mul_f32 v[60:61], v[60:61], v[140:141]
	v_pk_mul_f32 v[62:63], v[62:63], v[142:143]
	v_pk_mul_f32 v[60:61], v[60:61], v[56:57]
	v_pk_mul_f32 v[62:63], v[62:63], v[58:59]
	v_pk_mul_f32 v[52:53], v[52:53], v[158:159] op_sel_hi:[1,0]
	v_pk_mul_f32 v[48:49], v[48:49], v[158:159] op_sel_hi:[1,0]
	v_pk_mul_f32 v[54:55], v[54:55], v[158:159] op_sel_hi:[1,0]
	v_pk_mul_f32 v[50:51], v[50:51], v[158:159] op_sel_hi:[1,0]
	v_pk_mul_f32 v[140:141], v[52:53], s[2:3] op_sel_hi:[1,0]
	v_pk_mul_f32 v[142:143], v[54:55], s[2:3] op_sel_hi:[1,0]
	v_exp_f32_e32 v140, v140
	v_exp_f32_e32 v141, v141
	v_exp_f32_e32 v142, v142
	v_exp_f32_e32 v143, v143
	v_pk_add_f32 v[140:141], v[140:141], 1.0 op_sel_hi:[1,0]
	v_pk_add_f32 v[142:143], v[142:143], 1.0 op_sel_hi:[1,0]
	v_rcp_f32_e32 v140, v140
	v_rcp_f32_e32 v141, v141
	v_rcp_f32_e32 v142, v142
	v_rcp_f32_e32 v143, v143
	v_pk_mul_f32 v[52:53], v[52:53], v[140:141]
	v_pk_mul_f32 v[54:55], v[54:55], v[142:143]
	v_pk_mul_f32 v[52:53], v[52:53], v[48:49]
	v_pk_mul_f32 v[54:55], v[54:55], v[50:51]
	v_cvt_pk_bf16_f32 v60, v60, v61
	v_cvt_pk_bf16_f32 v61, v62, v63
	v_cvt_pk_bf16_f32 v62, v52, v53
	v_cvt_pk_bf16_f32 v63, v54, v55
	v_add_u32_e32 v149, 0xb0000, v171
	global_store_dwordx4 v149, v[60:63], s[10:11]
	v_pk_mul_f32 v[44:45], v[44:45], v[160:161] op_sel_hi:[1,0]
; #define PG8_BAR __builtin_amdgcn_s_barrier()
; #define PG8_ZERO_ACC() do { _Pragma("unroll") for (int a = 0; a < 2; ++a) _Pragma("unroll") for (int b = 0; b < 2; ++b) _Pragma("unroll") for (int m = 0; m < 4; ++m) _Pragma("unroll") for (int n = 0; n < 2; ++n) acc[a][b][m][n] = (f32x4){0.f, 0.f, 0.f, 0.f}; } while (0)
; __device__ __forceinline__ unsigned pk2(float lo, float hi) { unsigned r; asm("v_cvt_pk_bf16_f32 %0, %1, %2" : "=v"(r) : "v"(lo), "v"(hi)); return r; }
; __device__ __forceinline__ float silu_f(float x) { return x * sigmoid_f(x); }
; template <class Epi, class Sched, bool ALIGN_EPI = false, bool SP2 = false>
; __device__ __forceinline__ void gemm_phase(PG8_LAS unsigned char* lds, const Gemm g, const Sched& S, const Epi& E, const int wave_s) {
;     ...
;         if (!has_next) break;
;     ...
;         if constexpr (Epi::INIT_ACC) {
;             if (Sched::STREAMK && nxt.kind == 2) S.load_partial(acc, tid, wid, lane);
;             else if (nxt.kind == 0) { int fr_i = fr, fq_i = fq; asm volatile("" : "+v"(fr_i), "+v"(fq_i)); E.init(acc, nxt, wr, wc, fr_i, fq_i); }
;             else PG8_ZERO_ACC();
;         } else {
;             if (Sched::STREAMK && nxt.kind == 2) S.load_partial(acc, tid, wid, lane);
;             else PG8_ZERO_ACC();
;         }
;     ...
;         cur = nxt; cA = nA; cB = nB; ++ui;
;         if constexpr (ALIGN_EPI) { if (wr == 1) PG8_BAR; }
;     __device__ __forceinline__ void operator()(const f32x4 (&acc)[2][2][4][2], const pg8::Unit& u, int wr, int wc, int fr, int fq) const {
;     ...
;         for (int ai = 0; ai < 2; ++ai)
; #pragma unroll
;             for (int m = 0; m < 4; ++m) {
;                 const int r = row0 + ai * 128 + m * 16;
;                 const float rstd = __builtin_amdgcn_rsqf(rs[ai][m] * (1.0f / D) + EPS);
;                 float o[8];
; #pragma unroll
;                 for (int n = 0; n < 2; ++n)
; #pragma unroll
;                     for (int e = 0; e < 4; ++e) { const float g = acc[ai][0][m][n][e] * rstd, up = acc[ai][1][m][n][e] * rstd; o[4 * n + e] = silu_f(g) * up; }
;                 u32x4 w; w.x = pk2(o[0], o[1]); w.y = pk2(o[2], o[3]); w.z = pk2(o[4], o[5]); w.w = pk2(o[6], o[7]);
;                 *(u32x4*)(ACT + (size_t)r * FF + col0) = w;
	v_pk_mul_f32 v[40:41], v[40:41], v[160:161] op_sel_hi:[1,0]
	v_pk_mul_f32 v[46:47], v[46:47], v[160:161] op_sel_hi:[1,0]
	v_pk_mul_f32 v[42:43], v[42:43], v[160:161] op_sel_hi:[1,0]
	v_pk_mul_f32 v[140:141], v[44:45], s[2:3] op_sel_hi:[1,0]
	v_pk_mul_f32 v[142:143], v[46:47], s[2:3] op_sel_hi:[1,0]
	v_exp_f32_e32 v140, v140
	v_exp_f32_e32 v141, v141
	v_exp_f32_e32 v142, v142
	v_exp_f32_e32 v143, v143
	v_pk_add_f32 v[140:141], v[140:141], 1.0 op_sel_hi:[1,0]
	v_pk_add_f32 v[142:143], v[142:143], 1.0 op_sel_hi:[1,0]
	v_rcp_f32_e32 v140, v140
	v_rcp_f32_e32 v141, v141
	v_rcp_f32_e32 v142, v142
	v_rcp_f32_e32 v143, v143
	v_pk_mul_f32 v[44:45], v[44:45], v[140:141]
	v_pk_mul_f32 v[46:47], v[46:47], v[142:143]
	v_pk_mul_f32 v[44:45], v[44:45], v[40:41]
	v_pk_mul_f32 v[46:47], v[46:47], v[42:43]
	v_pk_mul_f32 v[36:37], v[36:37], v[160:161] op_sel_hi:[1,0]
	v_pk_mul_f32 v[32:33], v[32:33], v[160:161] op_sel_hi:[1,0]
	v_pk_mul_f32 v[38:39], v[38:39], v[160:161] op_sel_hi:[1,0]
	v_pk_mul_f32 v[34:35], v[34:35], v[160:161] op_sel_hi:[1,0]
	v_pk_mul_f32 v[140:141], v[36:37], s[2:3] op_sel_hi:[1,0]
	v_pk_mul_f32 v[142:143], v[38:39], s[2:3] op_sel_hi:[1,0]
	v_exp_f32_e32 v140, v140
	v_exp_f32_e32 v141, v141
	v_exp_f32_e32 v142, v142
	v_exp_f32_e32 v143, v143
	v_pk_add_f32 v[140:141], v[140:141], 1.0 op_sel_hi:[1,0]
	v_pk_add_f32 v[142:143], v[142:143], 1.0 op_sel_hi:[1,0]
	v_rcp_f32_e32 v140, v140
	v_rcp_f32_e32 v141, v141
	v_rcp_f32_e32 v142, v142
	v_rcp_f32_e32 v143, v143
	v_pk_mul_f32 v[36:37], v[36:37], v[140:141]
	v_pk_mul_f32 v[38:39], v[38:39], v[142:143]
	v_pk_mul_f32 v[36:37], v[36:37], v[32:33]
	v_pk_mul_f32 v[38:39], v[38:39], v[34:35]
	v_cvt_pk_bf16_f32 v44, v44, v45
	v_cvt_pk_bf16_f32 v45, v46, v47
	v_cvt_pk_bf16_f32 v46, v36, v37
	v_cvt_pk_bf16_f32 v47, v38, v39
	v_add_u32_e32 v149, 0xc6000, v171
	global_store_dwordx4 v149, v[44:47], s[10:11]
	v_pk_mul_f32 v[28:29], v[28:29], v[144:145] op_sel_hi:[1,0]
	v_pk_mul_f32 v[24:25], v[24:25], v[144:145] op_sel_hi:[1,0]
	v_pk_mul_f32 v[30:31], v[30:31], v[144:145] op_sel_hi:[1,0]
	v_pk_mul_f32 v[26:27], v[26:27], v[144:145] op_sel_hi:[1,0]
	v_pk_mul_f32 v[140:141], v[28:29], s[2:3] op_sel_hi:[1,0]
	v_pk_mul_f32 v[142:143], v[30:31], s[2:3] op_sel_hi:[1,0]
	v_exp_f32_e32 v140, v140
	v_exp_f32_e32 v141, v141
	v_exp_f32_e32 v142, v142
	v_exp_f32_e32 v143, v143
	v_pk_add_f32 v[140:141], v[140:141], 1.0 op_sel_hi:[1,0]
	v_pk_add_f32 v[142:143], v[142:143], 1.0 op_sel_hi:[1,0]
	v_rcp_f32_e32 v140, v140
	v_rcp_f32_e32 v141, v141
	v_rcp_f32_e32 v142, v142
	v_rcp_f32_e32 v143, v143
	v_pk_mul_f32 v[28:29], v[28:29], v[140:141]
	v_pk_mul_f32 v[30:31], v[30:31], v[142:143]
	v_pk_mul_f32 v[28:29], v[28:29], v[24:25]
	v_pk_mul_f32 v[30:31], v[30:31], v[26:27]
	v_pk_mul_f32 v[20:21], v[20:21], v[144:145] op_sel_hi:[1,0]
	v_pk_mul_f32 v[16:17], v[16:17], v[144:145] op_sel_hi:[1,0]
	v_pk_mul_f32 v[22:23], v[22:23], v[144:145] op_sel_hi:[1,0]
	v_pk_mul_f32 v[18:19], v[18:19], v[144:145] op_sel_hi:[1,0]
	v_pk_mul_f32 v[140:141], v[20:21], s[2:3] op_sel_hi:[1,0]
	v_pk_mul_f32 v[142:143], v[22:23], s[2:3] op_sel_hi:[1,0]
	v_exp_f32_e32 v140, v140
	v_exp_f32_e32 v141, v141
	v_exp_f32_e32 v142, v142
	v_exp_f32_e32 v143, v143
	v_pk_add_f32 v[140:141], v[140:141], 1.0 op_sel_hi:[1,0]
	v_pk_add_f32 v[142:143], v[142:143], 1.0 op_sel_hi:[1,0]
	v_rcp_f32_e32 v140, v140
	v_rcp_f32_e32 v141, v141
	v_rcp_f32_e32 v142, v142
	v_rcp_f32_e32 v143, v143
	v_pk_mul_f32 v[20:21], v[20:21], v[140:141]
	v_pk_mul_f32 v[22:23], v[22:23], v[142:143]
	v_pk_mul_f32 v[20:21], v[20:21], v[16:17]
	v_pk_mul_f32 v[22:23], v[22:23], v[18:19]
	v_cvt_pk_bf16_f32 v28, v28, v29
	v_cvt_pk_bf16_f32 v29, v30, v31
	v_cvt_pk_bf16_f32 v30, v20, v21
	v_cvt_pk_bf16_f32 v31, v22, v23
	v_add_u32_e32 v149, 0xdc000, v171
	global_store_dwordx4 v149, v[28:31], s[10:11]
	v_pk_mul_f32 v[12:13], v[12:13], v[174:175] op_sel_hi:[1,0]
	v_pk_mul_f32 v[8:9], v[8:9], v[174:175] op_sel_hi:[1,0]
	v_pk_mul_f32 v[14:15], v[14:15], v[174:175] op_sel_hi:[1,0]
	v_pk_mul_f32 v[10:11], v[10:11], v[174:175] op_sel_hi:[1,0]
	v_pk_mul_f32 v[140:141], v[12:13], s[2:3] op_sel_hi:[1,0]
	v_pk_mul_f32 v[142:143], v[14:15], s[2:3] op_sel_hi:[1,0]
	v_exp_f32_e32 v140, v140
	v_exp_f32_e32 v141, v141
	v_exp_f32_e32 v142, v142
	v_exp_f32_e32 v143, v143
	v_pk_add_f32 v[140:141], v[140:141], 1.0 op_sel_hi:[1,0]
	v_pk_add_f32 v[142:143], v[142:143], 1.0 op_sel_hi:[1,0]
	v_rcp_f32_e32 v140, v140
	v_rcp_f32_e32 v141, v141
	v_rcp_f32_e32 v142, v142
	v_rcp_f32_e32 v143, v143
	v_pk_mul_f32 v[12:13], v[12:13], v[140:141]
	v_pk_mul_f32 v[14:15], v[14:15], v[142:143]
	v_pk_mul_f32 v[12:13], v[12:13], v[8:9]
	v_pk_mul_f32 v[14:15], v[14:15], v[10:11]
	v_pk_mul_f32 v[4:5], v[4:5], v[174:175] op_sel_hi:[1,0]
	v_pk_mul_f32 v[0:1], v[0:1], v[174:175] op_sel_hi:[1,0]
	v_pk_mul_f32 v[6:7], v[6:7], v[174:175] op_sel_hi:[1,0]
	v_pk_mul_f32 v[2:3], v[2:3], v[174:175] op_sel_hi:[1,0]
	v_pk_mul_f32 v[140:141], v[4:5], s[2:3] op_sel_hi:[1,0]
	v_pk_mul_f32 v[142:143], v[6:7], s[2:3] op_sel_hi:[1,0]
	v_exp_f32_e32 v140, v140
	v_exp_f32_e32 v141, v141
	v_exp_f32_e32 v142, v142
	v_exp_f32_e32 v143, v143
	v_pk_add_f32 v[140:141], v[140:141], 1.0 op_sel_hi:[1,0]
	v_pk_add_f32 v[142:143], v[142:143], 1.0 op_sel_hi:[1,0]
	v_rcp_f32_e32 v140, v140
	v_rcp_f32_e32 v141, v141
	v_rcp_f32_e32 v142, v142
	v_rcp_f32_e32 v143, v143
	v_pk_mul_f32 v[4:5], v[4:5], v[140:141]
	v_pk_mul_f32 v[6:7], v[6:7], v[142:143]
	v_pk_mul_f32 v[4:5], v[4:5], v[0:1]
	v_pk_mul_f32 v[6:7], v[6:7], v[2:3]
	v_cvt_pk_bf16_f32 v12, v12, v13
	v_cvt_pk_bf16_f32 v13, v14, v15
	v_cvt_pk_bf16_f32 v14, v4, v5
	v_cvt_pk_bf16_f32 v15, v6, v7
	v_add_u32_e32 v149, 0xf2000, v171
	global_store_dwordx4 v149, v[12:15], s[10:11]
	s_mov_b64 s[2:3], -1
	s_andn2_b64 vcc, exec, s[6:7]
	s_cbranch_vccnz .LBB0_515
	s_andn2_b64 vcc, exec, s[8:9]
	s_cbranch_vccnz .LBB0_514
	s_barrier
	s_branch .LBB0_514
